# m14 + grid barrier: non-last arrivers issue the L1 acquire invalidate before the spin instead of after it (XCD leader keeps its post-barrier invalidate)
# speedup vs baseline: 1.0037x; 1.0037x over previous
; __device__ __forceinline__ unsigned xb_ld(unsigned* p)              { return __hip_atomic_load(p, __ATOMIC_RELAXED, __HIP_MEMORY_SCOPE_AGENT); }
; __device__ __forceinline__ unsigned xb_add(unsigned* p, unsigned v) { return __hip_atomic_fetch_add(p, v, __ATOMIC_RELAXED, __HIP_MEMORY_SCOPE_AGENT); }
; #define XB_SPIN(cond, bar) do { unsigned _sp = 0; while (cond) { __builtin_amdgcn_s_sleep(1); \
;     if ((++_sp & 255u) == 0u) { if (xb_ld(&(bar)[XB_TMO])) break; if (_sp > XB_SPIN_CAP) { atomicAdd(&(bar)[XB_TMO], 1u); break; } } } } while (0)
; __device__ __forceinline__ void xcd_barrier(const XcdBarrier& b) {
;     ...
;         const unsigned old = xb_add(&bar[XB_XSUB(b.x)], 1u);
;         const unsigned gen = old / nloc;
;         if (old + 1u == (gen + 1u) * nloc) {
;             __builtin_amdgcn_fence(__ATOMIC_RELEASE, "agent");
;             asm volatile("s_waitcnt vmcnt(0)" ::: "memory");
;             const unsigned og = xb_add(&bar[XB_TOP], 1u);
;             const unsigned tg = og / nx;
;             if (og + 1u == (tg + 1u) * nx) xb_add(&bar[XB_TOPGEN], 1u);
;             else XB_SPIN(xb_ld(&bar[XB_TOPGEN]) == tg, bar);
;             __builtin_amdgcn_fence(__ATOMIC_ACQUIRE, "agent");
;             xb_add(&bar[XB_XGEN(b.x)], 1u);
;             asm volatile("s_waitcnt vmcnt(0)" ::: "memory");
;         } else {
;             XB_SPIN(xb_ld(&bar[XB_XGEN(b.x)]) == gen, bar);
;             __builtin_amdgcn_fence(__ATOMIC_ACQUIRE, "agent");
;             asm volatile("s_waitcnt vmcnt(0)" ::: "memory");
.LBB11_180:
	s_or_b64 exec, exec, s[12:13]
	v_cvt_f32_u32_e32 v5, v3
	s_waitcnt vmcnt(0)
	v_readfirstlane_b32 s10, v4
	s_add_u32 s8, s8, 0x2400
	s_addc_u32 s9, s9, 0
	v_rcp_iflag_f32_e32 v5, v5
	v_add_u32_e32 v6, s10, v2
	v_mul_f32_e32 v4, 0x4f7ffffe, v5
	v_cvt_u32_f32_e32 v4, v4
	v_sub_u32_e32 v5, 0, v3
	v_mul_lo_u32 v2, v5, v4
	v_mul_hi_u32 v2, v4, v2
	v_add_u32_e32 v2, v4, v2
	v_mul_hi_u32 v2, v6, v2
	v_mul_lo_u32 v4, v2, v3
	v_sub_u32_e32 v4, v6, v4
	v_add_u32_e32 v5, 1, v2
	v_cmp_ge_u32_e32 vcc, v4, v3
	s_nop 1
	v_cndmask_b32_e32 v2, v2, v5, vcc
	v_sub_u32_e32 v5, v4, v3
	v_cndmask_b32_e32 v4, v4, v5, vcc
	v_add_u32_e32 v5, 1, v2
	v_cmp_ge_u32_e32 vcc, v4, v3
	v_add_u32_e32 v4, 1, v6
	s_nop 0
	v_cndmask_b32_e32 v2, v2, v5, vcc
	v_mul_lo_u32 v5, v3, v2
	v_add_u32_e32 v3, v5, v3
	v_cmp_ne_u32_e32 vcc, v4, v3
	s_and_saveexec_b64 s[10:11], vcc
	s_xor_b64 s[10:11], exec, s[10:11]
	s_cbranch_execz .LBB11_194
	s_waitcnt lgkmcnt(0)
	v_mov_b32_e32 v1, 0
	buffer_inv sc1
	global_load_dword v3, v1, s[8:9] sc1
	s_waitcnt vmcnt(0)
	v_cmp_eq_u32_e32 vcc, v3, v2
	s_and_saveexec_b64 s[12:13], vcc
	s_cbranch_execz .LBB11_193
	s_mov_b32 s24, 1
	s_mov_b64 s[14:15], 0
	s_branch .LBB11_184

; __device__ __forceinline__ unsigned xb_ld(unsigned* p)              { return __hip_atomic_load(p, __ATOMIC_RELAXED, __HIP_MEMORY_SCOPE_AGENT); }
; #define XB_SPIN(cond, bar) do { unsigned _sp = 0; while (cond) { __builtin_amdgcn_s_sleep(1); \
;     if ((++_sp & 255u) == 0u) { if (xb_ld(&(bar)[XB_TMO])) break; if (_sp > XB_SPIN_CAP) { atomicAdd(&(bar)[XB_TMO], 1u); break; } } } } while (0)
; __device__ __forceinline__ void xcd_barrier(const XcdBarrier& b) {
;     ...
;             XB_SPIN(xb_ld(&bar[XB_XGEN(b.x)]) == gen, bar);
;             __builtin_amdgcn_fence(__ATOMIC_ACQUIRE, "agent");
;             asm volatile("s_waitcnt vmcnt(0)" ::: "memory");
.LBB11_193:
	s_or_b64 exec, exec, s[12:13]
	s_waitcnt vmcnt(0)
	s_waitcnt vmcnt(0)

; __device__ __forceinline__ unsigned xb_ld(unsigned* p)              { return __hip_atomic_load(p, __ATOMIC_RELAXED, __HIP_MEMORY_SCOPE_AGENT); }
; __device__ __forceinline__ unsigned xb_add(unsigned* p, unsigned v) { return __hip_atomic_fetch_add(p, v, __ATOMIC_RELAXED, __HIP_MEMORY_SCOPE_AGENT); }
; #define XB_SPIN(cond, bar) do { unsigned _sp = 0; while (cond) { __builtin_amdgcn_s_sleep(1); \
;     if ((++_sp & 255u) == 0u) { if (xb_ld(&(bar)[XB_TMO])) break; if (_sp > XB_SPIN_CAP) { atomicAdd(&(bar)[XB_TMO], 1u); break; } } } } while (0)
; __device__ __forceinline__ void xcd_barrier(const XcdBarrier& b) {
;     ...
;         const unsigned old = xb_add(&bar[XB_XSUB(b.x)], 1u);
;         const unsigned gen = old / nloc;
;         if (old + 1u == (gen + 1u) * nloc) {
;             __builtin_amdgcn_fence(__ATOMIC_RELEASE, "agent");
;             asm volatile("s_waitcnt vmcnt(0)" ::: "memory");
;             const unsigned og = xb_add(&bar[XB_TOP], 1u);
;             const unsigned tg = og / nx;
;             if (og + 1u == (tg + 1u) * nx) xb_add(&bar[XB_TOPGEN], 1u);
;             else XB_SPIN(xb_ld(&bar[XB_TOPGEN]) == tg, bar);
;             __builtin_amdgcn_fence(__ATOMIC_ACQUIRE, "agent");
;             xb_add(&bar[XB_XGEN(b.x)], 1u);
;             asm volatile("s_waitcnt vmcnt(0)" ::: "memory");
;         } else {
;             XB_SPIN(xb_ld(&bar[XB_XGEN(b.x)]) == gen, bar);
.LBB11_395:
	s_or_b64 exec, exec, s[6:7]
	v_cvt_f32_u32_e32 v6, v4
	s_waitcnt vmcnt(0)
	v_readfirstlane_b32 s1, v5
	v_sub_u32_e32 v5, 0, v4
	v_rcp_iflag_f32_e32 v6, v6
	v_add_u32_e32 v7, s1, v1
	v_mul_f32_e32 v6, 0x4f7ffffe, v6
	v_cvt_u32_f32_e32 v6, v6
	v_mul_lo_u32 v1, v5, v6
	v_mul_hi_u32 v1, v6, v1
	v_add_u32_e32 v1, v6, v1
	v_mul_hi_u32 v1, v7, v1
	v_mul_lo_u32 v5, v1, v4
	v_sub_u32_e32 v5, v7, v5
	v_add_u32_e32 v6, 1, v1
	v_cmp_ge_u32_e32 vcc, v5, v4
	s_nop 1
	v_cndmask_b32_e32 v1, v1, v6, vcc
	v_sub_u32_e32 v6, v5, v4
	v_cndmask_b32_e32 v5, v5, v6, vcc
	v_add_u32_e32 v6, 1, v1
	v_cmp_ge_u32_e32 vcc, v5, v4
	v_add_u32_e32 v5, 1, v7
	s_nop 0
	v_cndmask_b32_e32 v1, v1, v6, vcc
	v_mul_lo_u32 v6, v4, v1
	v_add_u32_e32 v4, v6, v4
	v_cmp_ne_u32_e32 vcc, v5, v4
	s_and_saveexec_b64 s[6:7], vcc
	s_xor_b64 s[6:7], exec, s[6:7]
	s_cbranch_execz .LBB11_409
	v_readlane_b32 s8, v250, 47
	v_readlane_b32 s9, v250, 48
	s_waitcnt lgkmcnt(0)
	s_nop 3
	buffer_inv sc1
	global_load_dword v2, v3, s[8:9] sc1
	s_waitcnt vmcnt(0)
	v_cmp_eq_u32_e32 vcc, v2, v1
	s_and_saveexec_b64 s[8:9], vcc
	s_cbranch_execz .LBB11_408
	s_mov_b32 s1, 1
	s_mov_b64 s[10:11], 0
	s_branch .LBB11_399

; __device__ __forceinline__ unsigned xb_ld(unsigned* p)              { return __hip_atomic_load(p, __ATOMIC_RELAXED, __HIP_MEMORY_SCOPE_AGENT); }
; #define XB_SPIN(cond, bar) do { unsigned _sp = 0; while (cond) { __builtin_amdgcn_s_sleep(1); \
;     if ((++_sp & 255u) == 0u) { if (xb_ld(&(bar)[XB_TMO])) break; if (_sp > XB_SPIN_CAP) { atomicAdd(&(bar)[XB_TMO], 1u); break; } } } } while (0)
; __device__ __forceinline__ void xcd_barrier(const XcdBarrier& b) {
;     ...
;             XB_SPIN(xb_ld(&bar[XB_XGEN(b.x)]) == gen, bar);
;             __builtin_amdgcn_fence(__ATOMIC_ACQUIRE, "agent");
;             asm volatile("s_waitcnt vmcnt(0)" ::: "memory");
.LBB11_408:
	s_or_b64 exec, exec, s[8:9]
	s_waitcnt vmcnt(0)
	s_waitcnt vmcnt(0)

; __device__ __forceinline__ unsigned xb_ld(unsigned* p)              { return __hip_atomic_load(p, __ATOMIC_RELAXED, __HIP_MEMORY_SCOPE_AGENT); }
; __device__ __forceinline__ unsigned xb_add(unsigned* p, unsigned v) { return __hip_atomic_fetch_add(p, v, __ATOMIC_RELAXED, __HIP_MEMORY_SCOPE_AGENT); }
; #define XB_SPIN(cond, bar) do { unsigned _sp = 0; while (cond) { __builtin_amdgcn_s_sleep(1); \
;     if ((++_sp & 255u) == 0u) { if (xb_ld(&(bar)[XB_TMO])) break; if (_sp > XB_SPIN_CAP) { atomicAdd(&(bar)[XB_TMO], 1u); break; } } } } while (0)
; __device__ __forceinline__ void xcd_barrier(const XcdBarrier& b) {
;     ...
;         const unsigned old = xb_add(&bar[XB_XSUB(b.x)], 1u);
;         const unsigned gen = old / nloc;
;         if (old + 1u == (gen + 1u) * nloc) {
;             __builtin_amdgcn_fence(__ATOMIC_RELEASE, "agent");
;             asm volatile("s_waitcnt vmcnt(0)" ::: "memory");
;             const unsigned og = xb_add(&bar[XB_TOP], 1u);
;             const unsigned tg = og / nx;
;             if (og + 1u == (tg + 1u) * nx) xb_add(&bar[XB_TOPGEN], 1u);
;             else XB_SPIN(xb_ld(&bar[XB_TOPGEN]) == tg, bar);
;             __builtin_amdgcn_fence(__ATOMIC_ACQUIRE, "agent");
;             xb_add(&bar[XB_XGEN(b.x)], 1u);
;             asm volatile("s_waitcnt vmcnt(0)" ::: "memory");
;         } else {
;             XB_SPIN(xb_ld(&bar[XB_XGEN(b.x)]) == gen, bar);
.LBB11_429:
	s_or_b64 exec, exec, s[4:5]
	v_cvt_f32_u32_e32 v6, v4
	s_waitcnt vmcnt(0)
	v_readfirstlane_b32 s1, v5
	v_sub_u32_e32 v5, 0, v4
	v_rcp_iflag_f32_e32 v6, v6
	v_add_u32_e32 v7, s1, v1
	v_mul_f32_e32 v6, 0x4f7ffffe, v6
	v_cvt_u32_f32_e32 v6, v6
	v_mul_lo_u32 v1, v5, v6
	v_mul_hi_u32 v1, v6, v1
	v_add_u32_e32 v1, v6, v1
	v_mul_hi_u32 v1, v7, v1
	v_mul_lo_u32 v5, v1, v4
	v_sub_u32_e32 v5, v7, v5
	v_add_u32_e32 v6, 1, v1
	v_cmp_ge_u32_e32 vcc, v5, v4
	s_nop 1
	v_cndmask_b32_e32 v1, v1, v6, vcc
	v_sub_u32_e32 v6, v5, v4
	v_cndmask_b32_e32 v5, v5, v6, vcc
	v_add_u32_e32 v6, 1, v1
	v_cmp_ge_u32_e32 vcc, v5, v4
	v_add_u32_e32 v5, 1, v7
	s_nop 0
	v_cndmask_b32_e32 v1, v1, v6, vcc
	v_mul_lo_u32 v6, v4, v1
	v_add_u32_e32 v4, v6, v4
	v_cmp_ne_u32_e32 vcc, v5, v4
	s_and_saveexec_b64 s[4:5], vcc
	s_xor_b64 s[4:5], exec, s[4:5]
	s_cbranch_execz .LBB11_604
	v_readlane_b32 s8, v250, 47
	v_readlane_b32 s9, v250, 48
	s_waitcnt lgkmcnt(0)
	s_nop 3
	buffer_inv sc1
	global_load_dword v2, v3, s[8:9] sc1
	s_waitcnt vmcnt(0)
	v_cmp_eq_u32_e32 vcc, v2, v1
	s_and_saveexec_b64 s[8:9], vcc
	s_cbranch_execz .LBB11_603
	s_mov_b32 s1, 1
	s_mov_b64 s[10:11], 0
	s_branch .LBB11_433

; __device__ __forceinline__ unsigned xb_ld(unsigned* p)              { return __hip_atomic_load(p, __ATOMIC_RELAXED, __HIP_MEMORY_SCOPE_AGENT); }
; __device__ __forceinline__ unsigned xb_add(unsigned* p, unsigned v) { return __hip_atomic_fetch_add(p, v, __ATOMIC_RELAXED, __HIP_MEMORY_SCOPE_AGENT); }
; #define XB_SPIN(cond, bar) do { unsigned _sp = 0; while (cond) { __builtin_amdgcn_s_sleep(1); \
;     if ((++_sp & 255u) == 0u) { if (xb_ld(&(bar)[XB_TMO])) break; if (_sp > XB_SPIN_CAP) { atomicAdd(&(bar)[XB_TMO], 1u); break; } } } } while (0)
; __device__ __forceinline__ void xcd_barrier(const XcdBarrier& b) {
;     ...
;         const unsigned old = xb_add(&bar[XB_XSUB(b.x)], 1u);
;         const unsigned gen = old / nloc;
;         if (old + 1u == (gen + 1u) * nloc) {
;             __builtin_amdgcn_fence(__ATOMIC_RELEASE, "agent");
;             asm volatile("s_waitcnt vmcnt(0)" ::: "memory");
;             const unsigned og = xb_add(&bar[XB_TOP], 1u);
;             const unsigned tg = og / nx;
;             if (og + 1u == (tg + 1u) * nx) xb_add(&bar[XB_TOPGEN], 1u);
;             else XB_SPIN(xb_ld(&bar[XB_TOPGEN]) == tg, bar);
;             __builtin_amdgcn_fence(__ATOMIC_ACQUIRE, "agent");
;             xb_add(&bar[XB_XGEN(b.x)], 1u);
;             asm volatile("s_waitcnt vmcnt(0)" ::: "memory");
;         } else {
;             XB_SPIN(xb_ld(&bar[XB_XGEN(b.x)]) == gen, bar);
.LBB11_869:
	s_or_b64 exec, exec, s[4:5]
	v_cvt_f32_u32_e32 v6, v4
	s_waitcnt vmcnt(0)
	v_readfirstlane_b32 s1, v5
	v_sub_u32_e32 v5, 0, v4
	v_rcp_iflag_f32_e32 v6, v6
	v_add_u32_e32 v7, s1, v1
	v_mul_f32_e32 v6, 0x4f7ffffe, v6
	v_cvt_u32_f32_e32 v6, v6
	v_mul_lo_u32 v1, v5, v6
	v_mul_hi_u32 v1, v6, v1
	v_add_u32_e32 v1, v6, v1
	v_mul_hi_u32 v1, v7, v1
	v_mul_lo_u32 v5, v1, v4
	v_sub_u32_e32 v5, v7, v5
	v_add_u32_e32 v6, 1, v1
	v_cmp_ge_u32_e32 vcc, v5, v4
	s_nop 1
	v_cndmask_b32_e32 v1, v1, v6, vcc
	v_sub_u32_e32 v6, v5, v4
	v_cndmask_b32_e32 v5, v5, v6, vcc
	v_add_u32_e32 v6, 1, v1
	v_cmp_ge_u32_e32 vcc, v5, v4
	v_add_u32_e32 v5, 1, v7
	s_nop 0
	v_cndmask_b32_e32 v1, v1, v6, vcc
	v_mul_lo_u32 v6, v4, v1
	v_add_u32_e32 v4, v6, v4
	v_cmp_ne_u32_e32 vcc, v5, v4
	s_and_saveexec_b64 s[4:5], vcc
	s_xor_b64 s[4:5], exec, s[4:5]
	s_cbranch_execz .LBB11_883
	v_readlane_b32 s6, v250, 47
	v_readlane_b32 s7, v250, 48
	s_waitcnt lgkmcnt(0)
	s_nop 3
	buffer_inv sc1
	global_load_dword v2, v3, s[6:7] sc1
	s_waitcnt vmcnt(0)
	v_cmp_eq_u32_e32 vcc, v2, v1
	s_and_saveexec_b64 s[6:7], vcc
	s_cbranch_execz .LBB11_882
	s_mov_b32 s1, 1
	s_mov_b64 s[8:9], 0
	s_branch .LBB11_873

; __device__ __forceinline__ unsigned xb_ld(unsigned* p)              { return __hip_atomic_load(p, __ATOMIC_RELAXED, __HIP_MEMORY_SCOPE_AGENT); }
; #define XB_SPIN(cond, bar) do { unsigned _sp = 0; while (cond) { __builtin_amdgcn_s_sleep(1); \
;     if ((++_sp & 255u) == 0u) { if (xb_ld(&(bar)[XB_TMO])) break; if (_sp > XB_SPIN_CAP) { atomicAdd(&(bar)[XB_TMO], 1u); break; } } } } while (0)
; __device__ __forceinline__ void xcd_barrier(const XcdBarrier& b) {
;     ...
;             XB_SPIN(xb_ld(&bar[XB_XGEN(b.x)]) == gen, bar);
;             __builtin_amdgcn_fence(__ATOMIC_ACQUIRE, "agent");
;             asm volatile("s_waitcnt vmcnt(0)" ::: "memory");
.LBB11_882:
	s_or_b64 exec, exec, s[6:7]
	s_waitcnt vmcnt(0)
	s_waitcnt vmcnt(0)

; __device__ __forceinline__ unsigned xb_ld(unsigned* p)              { return __hip_atomic_load(p, __ATOMIC_RELAXED, __HIP_MEMORY_SCOPE_AGENT); }
; __device__ __forceinline__ unsigned xb_add(unsigned* p, unsigned v) { return __hip_atomic_fetch_add(p, v, __ATOMIC_RELAXED, __HIP_MEMORY_SCOPE_AGENT); }
; #define XB_SPIN(cond, bar) do { unsigned _sp = 0; while (cond) { __builtin_amdgcn_s_sleep(1); \
;     if ((++_sp & 255u) == 0u) { if (xb_ld(&(bar)[XB_TMO])) break; if (_sp > XB_SPIN_CAP) { atomicAdd(&(bar)[XB_TMO], 1u); break; } } } } while (0)
; __device__ __forceinline__ void xcd_barrier(const XcdBarrier& b) {
;     ...
;         const unsigned old = xb_add(&bar[XB_XSUB(b.x)], 1u);
;         const unsigned gen = old / nloc;
;         if (old + 1u == (gen + 1u) * nloc) {
;             __builtin_amdgcn_fence(__ATOMIC_RELEASE, "agent");
;             asm volatile("s_waitcnt vmcnt(0)" ::: "memory");
;             const unsigned og = xb_add(&bar[XB_TOP], 1u);
;             const unsigned tg = og / nx;
;             if (og + 1u == (tg + 1u) * nx) xb_add(&bar[XB_TOPGEN], 1u);
;             else XB_SPIN(xb_ld(&bar[XB_TOPGEN]) == tg, bar);
;             __builtin_amdgcn_fence(__ATOMIC_ACQUIRE, "agent");
;             xb_add(&bar[XB_XGEN(b.x)], 1u);
;             asm volatile("s_waitcnt vmcnt(0)" ::: "memory");
;         } else {
;             XB_SPIN(xb_ld(&bar[XB_XGEN(b.x)]) == gen, bar);
.LBB11_1688:
	s_or_b64 exec, exec, s[4:5]
	v_cvt_f32_u32_e32 v6, v4
	s_waitcnt vmcnt(0)
	v_readfirstlane_b32 s1, v5
	v_sub_u32_e32 v5, 0, v4
	v_rcp_iflag_f32_e32 v6, v6
	v_add_u32_e32 v7, s1, v1
	v_mul_f32_e32 v6, 0x4f7ffffe, v6
	v_cvt_u32_f32_e32 v6, v6
	v_mul_lo_u32 v1, v5, v6
	v_mul_hi_u32 v1, v6, v1
	v_add_u32_e32 v1, v6, v1
	v_mul_hi_u32 v1, v7, v1
	v_mul_lo_u32 v5, v1, v4
	v_sub_u32_e32 v5, v7, v5
	v_add_u32_e32 v6, 1, v1
	v_cmp_ge_u32_e32 vcc, v5, v4
	s_nop 1
	v_cndmask_b32_e32 v1, v1, v6, vcc
	v_sub_u32_e32 v6, v5, v4
	v_cndmask_b32_e32 v5, v5, v6, vcc
	v_add_u32_e32 v6, 1, v1
	v_cmp_ge_u32_e32 vcc, v5, v4
	v_add_u32_e32 v5, 1, v7
	s_nop 0
	v_cndmask_b32_e32 v1, v1, v6, vcc
	v_mul_lo_u32 v6, v4, v1
	v_add_u32_e32 v4, v6, v4
	v_cmp_ne_u32_e32 vcc, v5, v4
	s_and_saveexec_b64 s[4:5], vcc
	s_xor_b64 s[4:5], exec, s[4:5]
	s_cbranch_execz .LBB11_1702
	v_readlane_b32 s14, v250, 47
	v_readlane_b32 s15, v250, 48
	s_waitcnt lgkmcnt(0)
	s_nop 3
	buffer_inv sc1
	global_load_dword v2, v3, s[14:15] sc1
	s_waitcnt vmcnt(0)
	v_cmp_eq_u32_e32 vcc, v2, v1
	s_and_saveexec_b64 s[14:15], vcc
	s_cbranch_execz .LBB11_1701
	s_mov_b32 s1, 1
	s_mov_b64 s[16:17], 0
	s_branch .LBB11_1692

; __device__ __forceinline__ unsigned xb_ld(unsigned* p)              { return __hip_atomic_load(p, __ATOMIC_RELAXED, __HIP_MEMORY_SCOPE_AGENT); }
; #define XB_SPIN(cond, bar) do { unsigned _sp = 0; while (cond) { __builtin_amdgcn_s_sleep(1); \
;     if ((++_sp & 255u) == 0u) { if (xb_ld(&(bar)[XB_TMO])) break; if (_sp > XB_SPIN_CAP) { atomicAdd(&(bar)[XB_TMO], 1u); break; } } } } while (0)
; __device__ __forceinline__ void xcd_barrier(const XcdBarrier& b) {
;     ...
;             XB_SPIN(xb_ld(&bar[XB_XGEN(b.x)]) == gen, bar);
;             __builtin_amdgcn_fence(__ATOMIC_ACQUIRE, "agent");
;             asm volatile("s_waitcnt vmcnt(0)" ::: "memory");
.LBB11_1701:
	s_or_b64 exec, exec, s[14:15]
	s_waitcnt vmcnt(0)
	s_waitcnt vmcnt(0)
